# attnA relative-position bias: v_mov + v_fmac per element replaced by one v_fma with the scale in an SGPR (92 sites)
# baseline (speedup 1.0000x reference)
; #define LAS __attribute__((address_space(3)))
; template <int NCT>
; __device__ __forceinline__ void qk_accum(f32x4 (&s)[NCT], const LAS unsigned char* Kt, int key_row0, const bf16x8 (&qf)[4], int fr, int fq) {
; #pragma unroll
;     for (int ct = 0; ct < NCT; ++ct)
; #pragma unroll
;         for (int ks = 0; ks < 4; ++ks) { const bf16x8 kf = *(const LAS bf16x8*)(Kt + (key_row0 + 16 * ct + fr) * AT_PITCH + 64 * ks + 16 * fq);
;             s[ct] = __builtin_amdgcn_mfma_f32_16x16x32_bf16(kf, qf[ks], s[ct], 0, 0, 0); if (ks == 3 && (ct & 1)) asm volatile("" ::: "memory"); }
; }
; __device__ __forceinline__ void attnA_item(const Frame& F, const Args& a, int item) {
;     ...
;     const int qq = 16 * (F.wave & 3) + fr;
;     const int qpos = (n0 + hb) * 64 + qq;
;     const size_t qrow = rowbase + (size_t)qpos * d + r;
;     bf16x8 qf[4];
; #pragma unroll
;     for (int ks = 0; ks < 4; ++ks) qf[ks] = *(const bf16x8*)(proj + qrow * NIN + C_Q + h * 128 + 32 * ks + 8 * fq);
;     __syncthreads();
;     f32x4 s[12];
; #pragma unroll
;     for (int ct = 0; ct < 12; ++ct) s[ct] = (f32x4){0.f, 0.f, 0.f, 0.f};
;     qk_accum<12>(s, R0, 64 * hb, qf, fr, fq);
.LBB0_292:
	s_or_b64 exec, exec, s[72:73]
	s_add_i32 s12, s12, s95
	v_or_b32_e32 v66, s12, v85
	v_lshlrev_b64 v[0:1], s11, v[66:67]
	v_lshl_add_u64 v[60:61], v[0:1], 0, s[8:9]
	v_mov_b64_e32 v[0:1], s[96:97]
	v_mad_u64_u32 v[0:1], s[8:9], v60, s93, v[0:1]
	v_mov_b32_e32 v2, v1
	v_mad_u64_u32 v[2:3], s[8:9], v61, s93, v[2:3]
	v_mov_b32_e32 v1, v2
	v_lshl_add_u64 v[0:1], s[0:1], 1, v[0:1]
	v_mov_b32_e32 v71, v67
	v_lshl_add_u64 v[0:1], v[0:1], 0, v[70:71]
	global_load_dwordx4 v[56:59], v[0:1], off
	global_load_dwordx4 v[52:55], v[0:1], off offset:64
	global_load_dwordx4 v[48:51], v[0:1], off offset:128
	s_nop 0
	global_load_dwordx4 v[0:3], v[0:1], off offset:192
	s_waitcnt lgkmcnt(0)
	s_barrier
	s_sub_i32 s1, s12, 64
	s_cmp_lg_u32 s12, 0
	v_readlane_b32 s14, v242, 44
	s_cselect_b64 s[8:9], -1, 0
	v_readlane_b32 s15, v242, 45
	s_and_b64 s[14:15], s[14:15], s[8:9]
	ds_read_b128 v[208:211], v195
	ds_read_b128 v[212:215], v195 offset:64
	ds_read_b128 v[216:219], v195 offset:128
	ds_read_b128 v[220:223], v195 offset:192
	ds_read_b128 v[224:227], v195 offset:4352
	ds_read_b128 v[228:231], v195 offset:4416
	ds_read_b128 v[232:235], v195 offset:4480
	ds_read_b128 v[236:239], v195 offset:4544
	ds_read_b128 v[244:247], v195 offset:8704
	ds_read_b128 v[248:251], v195 offset:8768
	ds_read_b128 v[252:255], v195 offset:8832
	s_waitcnt vmcnt(0)
	s_waitcnt lgkmcnt(10)
	v_mfma_f32_16x16x32_bf16 v[4:7], v[208:211], v[56:59], 0
	ds_read_b128 v[208:211], v195 offset:8896
	s_waitcnt lgkmcnt(10)
	v_mfma_f32_16x16x32_bf16 v[4:7], v[212:215], v[52:55], v[4:7]
	ds_read_b128 v[212:215], v195 offset:13056
	s_waitcnt lgkmcnt(10)
	v_mfma_f32_16x16x32_bf16 v[4:7], v[216:219], v[48:51], v[4:7]
	ds_read_b128 v[216:219], v195 offset:13120
	s_waitcnt lgkmcnt(10)
	v_mfma_f32_16x16x32_bf16 v[44:47], v[220:223], v[0:3], v[4:7]
	ds_read_b128 v[220:223], v195 offset:13184
	s_waitcnt lgkmcnt(10)
	v_mfma_f32_16x16x32_bf16 v[4:7], v[224:227], v[56:59], 0
	ds_read_b128 v[224:227], v195 offset:13248
	s_waitcnt lgkmcnt(10)
	v_mfma_f32_16x16x32_bf16 v[4:7], v[228:231], v[52:55], v[4:7]
	ds_read_b128 v[228:231], v195 offset:17408
	s_waitcnt lgkmcnt(10)
	v_mfma_f32_16x16x32_bf16 v[4:7], v[232:235], v[48:51], v[4:7]
	ds_read_b128 v[232:235], v195 offset:17472
	s_waitcnt lgkmcnt(10)
	v_mfma_f32_16x16x32_bf16 v[40:43], v[236:239], v[0:3], v[4:7]
	ds_read_b128 v[236:239], v195 offset:17536
	s_waitcnt lgkmcnt(10)
	v_mfma_f32_16x16x32_bf16 v[4:7], v[244:247], v[56:59], 0
	ds_read_b128 v[244:247], v195 offset:17600
	s_waitcnt lgkmcnt(10)
	v_mfma_f32_16x16x32_bf16 v[4:7], v[248:251], v[52:55], v[4:7]
	ds_read_b128 v[248:251], v195 offset:21760
	s_waitcnt lgkmcnt(10)
	v_mfma_f32_16x16x32_bf16 v[4:7], v[252:255], v[48:51], v[4:7]
	ds_read_b128 v[252:255], v195 offset:21824
	s_waitcnt lgkmcnt(10)
	v_mfma_f32_16x16x32_bf16 v[36:39], v[208:211], v[0:3], v[4:7]
	ds_read_b128 v[208:211], v195 offset:21888
	s_waitcnt lgkmcnt(10)
	v_mfma_f32_16x16x32_bf16 v[4:7], v[212:215], v[56:59], 0
	ds_read_b128 v[212:215], v195 offset:21952
	s_waitcnt lgkmcnt(10)
	v_mfma_f32_16x16x32_bf16 v[4:7], v[216:219], v[52:55], v[4:7]
	ds_read_b128 v[216:219], v195 offset:26112
	s_waitcnt lgkmcnt(10)
	v_mfma_f32_16x16x32_bf16 v[4:7], v[220:223], v[48:51], v[4:7]
	ds_read_b128 v[220:223], v195 offset:26176
	s_waitcnt lgkmcnt(10)
	v_mfma_f32_16x16x32_bf16 v[32:35], v[224:227], v[0:3], v[4:7]
	ds_read_b128 v[224:227], v195 offset:26240
	s_waitcnt lgkmcnt(10)
	v_mfma_f32_16x16x32_bf16 v[4:7], v[228:231], v[56:59], 0
	ds_read_b128 v[228:231], v195 offset:26304
	s_waitcnt lgkmcnt(10)
	v_mfma_f32_16x16x32_bf16 v[4:7], v[232:235], v[52:55], v[4:7]
	ds_read_b128 v[232:235], v195 offset:30464
	s_waitcnt lgkmcnt(10)
	v_mfma_f32_16x16x32_bf16 v[4:7], v[236:239], v[48:51], v[4:7]
	ds_read_b128 v[236:239], v195 offset:30528
	s_waitcnt lgkmcnt(10)
	v_mfma_f32_16x16x32_bf16 v[20:23], v[244:247], v[0:3], v[4:7]
	ds_read_b128 v[244:247], v195 offset:30592
	s_waitcnt lgkmcnt(10)
	v_mfma_f32_16x16x32_bf16 v[4:7], v[248:251], v[56:59], 0
	ds_read_b128 v[248:251], v195 offset:30656
	s_waitcnt lgkmcnt(10)
	v_mfma_f32_16x16x32_bf16 v[4:7], v[252:255], v[52:55], v[4:7]
	ds_read_b128 v[252:255], v195 offset:34816
	s_waitcnt lgkmcnt(10)
	v_mfma_f32_16x16x32_bf16 v[4:7], v[208:211], v[48:51], v[4:7]
	ds_read_b128 v[208:211], v195 offset:34880
	s_waitcnt lgkmcnt(10)
	v_mfma_f32_16x16x32_bf16 v[16:19], v[212:215], v[0:3], v[4:7]
	ds_read_b128 v[212:215], v195 offset:34944
	s_waitcnt lgkmcnt(10)
	v_mfma_f32_16x16x32_bf16 v[4:7], v[216:219], v[56:59], 0
	ds_read_b128 v[216:219], v195 offset:35008
	s_waitcnt lgkmcnt(10)
	v_mfma_f32_16x16x32_bf16 v[4:7], v[220:223], v[52:55], v[4:7]
	ds_read_b128 v[220:223], v195 offset:39168
	s_waitcnt lgkmcnt(10)
	v_mfma_f32_16x16x32_bf16 v[4:7], v[224:227], v[48:51], v[4:7]
	ds_read_b128 v[224:227], v195 offset:39232
	s_waitcnt lgkmcnt(10)
	v_mfma_f32_16x16x32_bf16 v[28:31], v[228:231], v[0:3], v[4:7]
	ds_read_b128 v[228:231], v195 offset:39296
	s_waitcnt lgkmcnt(10)
	v_mfma_f32_16x16x32_bf16 v[4:7], v[232:235], v[56:59], 0
	ds_read_b128 v[232:235], v195 offset:39360
	s_waitcnt lgkmcnt(10)
	v_mfma_f32_16x16x32_bf16 v[4:7], v[236:239], v[52:55], v[4:7]
	ds_read_b128 v[236:239], v195 offset:43584
	s_waitcnt lgkmcnt(10)
	v_mfma_f32_16x16x32_bf16 v[4:7], v[244:247], v[48:51], v[4:7]
	ds_read_b128 v[244:247], v195 offset:43520
	s_waitcnt lgkmcnt(10)
	v_mfma_f32_16x16x32_bf16 v[24:27], v[248:251], v[0:3], v[4:7]
	ds_read_b128 v[248:251], v195 offset:43648
	s_waitcnt lgkmcnt(10)
	v_mfma_f32_16x16x32_bf16 v[4:7], v[252:255], v[56:59], 0
	ds_read_b128 v[252:255], v195 offset:43712
	s_waitcnt lgkmcnt(10)
; #define LAS __attribute__((address_space(3)))
; template <int NCT>
; __device__ __forceinline__ void qk_accum(f32x4 (&s)[NCT], const LAS unsigned char* Kt, int key_row0, const bf16x8 (&qf)[4], int fr, int fq) {
; #pragma unroll
;     for (int ct = 0; ct < NCT; ++ct)
; #pragma unroll
;         for (int ks = 0; ks < 4; ++ks) { const bf16x8 kf = *(const LAS bf16x8*)(Kt + (key_row0 + 16 * ct + fr) * AT_PITCH + 64 * ks + 16 * fq);
;             s[ct] = __builtin_amdgcn_mfma_f32_16x16x32_bf16(kf, qf[ks], s[ct], 0, 0, 0); if (ks == 3 && (ct & 1)) asm volatile("" ::: "memory"); }
; }
; __device__ __forceinline__ void attnA_item(const Frame& F, const Args& a, int item) {
;     ...
;     for (int ct = 0; ct < 12; ++ct)
; #pragma unroll
;         for (int j = 0; j < 4; ++j) { const int kk = 16 * ct + 4 * fq + j; const int rel = kk - 64 - qq; const int kp = kpw + kk;
;             const bool valid = (rel >= -64) && (rel <= 64) && (kp >= 0) && (kp < L);
;             const float bias = tab[valid ? rel + 64 : 64];
;             const float l = valid ? s[ct][j] * scale + bias : -1e30f; s[ct][j] = l; mx = fmaxf(mx, l); }
	v_mfma_f32_16x16x32_bf16 v[4:7], v[208:211], v[52:55], v[4:7]
	ds_read_b128 v[208:211], v195 offset:47872
	s_waitcnt lgkmcnt(10)
	v_mfma_f32_16x16x32_bf16 v[4:7], v[212:215], v[48:51], v[4:7]
	ds_read_b128 v[212:215], v195 offset:47936
	s_waitcnt lgkmcnt(10)
	v_mfma_f32_16x16x32_bf16 v[12:15], v[216:219], v[0:3], v[4:7]
	ds_read_b128 v[216:219], v195 offset:48000
	s_waitcnt lgkmcnt(10)
	v_mfma_f32_16x16x32_bf16 v[4:7], v[220:223], v[56:59], 0
	ds_read_b128 v[220:223], v195 offset:48064
	s_waitcnt lgkmcnt(10)
	v_mfma_f32_16x16x32_bf16 v[4:7], v[224:227], v[52:55], v[4:7]
	s_waitcnt lgkmcnt(9)
	v_mfma_f32_16x16x32_bf16 v[4:7], v[228:231], v[48:51], v[4:7]
	s_waitcnt lgkmcnt(8)
	v_mfma_f32_16x16x32_bf16 v[8:11], v[232:235], v[0:3], v[4:7]
	s_waitcnt lgkmcnt(6)
	v_mfma_f32_16x16x32_bf16 v[4:7], v[244:247], v[56:59], 0
	s_waitcnt lgkmcnt(7)
	v_mfma_f32_16x16x32_bf16 v[4:7], v[236:239], v[52:55], v[4:7]
	s_waitcnt lgkmcnt(5)
	v_mfma_f32_16x16x32_bf16 v[4:7], v[248:251], v[48:51], v[4:7]
	s_waitcnt lgkmcnt(4)
	v_mfma_f32_16x16x32_bf16 v[4:7], v[252:255], v[0:3], v[4:7]
	s_waitcnt lgkmcnt(3)
	v_mfma_f32_16x16x32_bf16 v[56:59], v[208:211], v[56:59], 0
	s_waitcnt lgkmcnt(2)
	v_mfma_f32_16x16x32_bf16 v[52:55], v[212:215], v[52:55], v[56:59]
	s_waitcnt lgkmcnt(1)
	v_mfma_f32_16x16x32_bf16 v[48:51], v[216:219], v[48:51], v[52:55]
	s_waitcnt lgkmcnt(0)
	v_mfma_f32_16x16x32_bf16 v[0:3], v[220:223], v[0:3], v[48:51]
	s_nop 2
	s_mov_b32 s99, 0x3db504f3
	ds_read_b32 v208, v86
	ds_read_b32 v209, v88
	ds_read_b32 v210, v90
	ds_read_b32 v211, v92
	ds_read_b32 v212, v94
	ds_read_b32 v213, v96
	ds_read_b32 v214, v98
	ds_read_b32 v215, v100
	ds_read_b32 v216, v102
	ds_read_b32 v217, v104
	ds_read_b32 v218, v106
	ds_read_b32 v219, v108
	ds_read_b32 v220, v110
	ds_read_b32 v221, v112
	ds_read_b32 v222, v114
	ds_read_b32 v223, v116
	ds_read_b32 v224, v117
	ds_read_b32 v225, v119
	ds_read_b32 v226, v121
	ds_read_b32 v227, v123
	ds_read_b32 v228, v125
	ds_read_b32 v229, v127
	ds_read_b32 v230, v129
	ds_read_b32 v231, v131
	ds_read_b32 v232, v133
	ds_read_b32 v233, v135
	ds_read_b32 v234, v137
	ds_read_b32 v235, v139
	ds_read_b32 v236, v141
	ds_read_b32 v237, v143
	ds_read_b32 v238, v146
	ds_read_b32 v239, v148
	ds_read_b32 v240, v150
	ds_read_b32 v241, v152
	ds_read_b32 v244, v154
	ds_read_b32 v245, v156
	ds_read_b32 v246, v158
	ds_read_b32 v247, v160
	ds_read_b32 v248, v162
	ds_read_b32 v249, v164
	ds_read_b32 v250, v166
	ds_read_b32 v251, v168
	ds_read_b32 v252, v170
	ds_read_b32 v253, v172
	ds_read_b32 v254, v174
	ds_read_b32 v255, v176
	s_waitcnt lgkmcnt(0)
	v_or_b32_e32 v48, s1, v68
	v_cmp_gt_i32_e32 vcc, s10, v48
	s_and_b64 s[14:15], s[14:15], vcc
	v_mov_b32_e32 v48, 0xf149f2ca
	v_mov_b32_e32 v49, 0xf149f2ca
	s_and_saveexec_b64 s[72:73], s[14:15]
	s_cbranch_execz .LBB0_294
	v_fma_f32 v49, v44, s99, v208
.LBB0_294:
	s_or_b64 exec, exec, s[72:73]
	v_readlane_b32 s14, v242, 46
	v_or_b32_e32 v44, s1, v87
	v_readlane_b32 s15, v242, 47
	s_and_b64 s[14:15], s[14:15], s[8:9]
	v_cmp_gt_i32_e32 vcc, s10, v44
	s_and_b64 s[14:15], s[14:15], vcc
	s_and_saveexec_b64 s[72:73], s[14:15]
	s_cbranch_execz .LBB0_296
	v_fma_f32 v48, v45, s99, v209
.LBB0_296:
	s_or_b64 exec, exec, s[72:73]
	v_readlane_b32 s14, v242, 48
	v_or_b32_e32 v44, s1, v89
	v_readlane_b32 s15, v242, 49
	s_and_b64 s[14:15], s[14:15], s[8:9]
	v_cmp_gt_i32_e32 vcc, s10, v44
	s_and_b64 s[14:15], s[14:15], vcc
	v_mov_b32_e32 v44, 0xf149f2ca
	v_mov_b32_e32 v45, 0xf149f2ca
	s_and_saveexec_b64 s[72:73], s[14:15]
	s_cbranch_execz .LBB0_298
	v_fma_f32 v45, v46, s99, v210
.LBB0_298:
	s_or_b64 exec, exec, s[72:73]
	v_readlane_b32 s14, v242, 50
	v_or_b32_e32 v46, s1, v91
	v_readlane_b32 s15, v242, 51
	s_and_b64 s[14:15], s[14:15], s[8:9]
	v_cmp_gt_i32_e32 vcc, s10, v46
	s_and_b64 s[14:15], s[14:15], vcc
	s_and_saveexec_b64 s[72:73], s[14:15]
	s_cbranch_execz .LBB0_300
	v_fma_f32 v44, v47, s99, v211
.LBB0_300:
	s_or_b64 exec, exec, s[72:73]
	v_readlane_b32 s14, v242, 52
	v_or_b32_e32 v46, s1, v93
	v_readlane_b32 s15, v242, 53
	s_and_b64 s[14:15], s[14:15], s[8:9]
	v_cmp_gt_i32_e32 vcc, s10, v46
	s_and_b64 s[14:15], s[14:15], vcc
	v_mov_b32_e32 v46, 0xf149f2ca
	v_mov_b32_e32 v47, 0xf149f2ca
	s_and_saveexec_b64 s[72:73], s[14:15]
	s_cbranch_execz .LBB0_302
	v_fma_f32 v47, v40, s99, v212
.LBB0_302:
	s_or_b64 exec, exec, s[72:73]
	v_readlane_b32 s14, v242, 54
	v_or_b32_e32 v40, s1, v95
	v_readlane_b32 s15, v242, 55
	s_and_b64 s[14:15], s[14:15], s[8:9]
	v_cmp_gt_i32_e32 vcc, s10, v40
	s_and_b64 s[14:15], s[14:15], vcc
	s_and_saveexec_b64 s[72:73], s[14:15]
	s_cbranch_execz .LBB0_304
	v_fma_f32 v46, v41, s99, v213
.LBB0_304:
	s_or_b64 exec, exec, s[72:73]
	v_readlane_b32 s14, v242, 56
	v_or_b32_e32 v40, s1, v97
	v_readlane_b32 s15, v242, 57
	s_and_b64 s[14:15], s[14:15], s[8:9]
	v_cmp_gt_i32_e32 vcc, s10, v40
	s_and_b64 s[14:15], s[14:15], vcc
	v_mov_b32_e32 v40, 0xf149f2ca
	v_mov_b32_e32 v41, 0xf149f2ca
	s_and_saveexec_b64 s[72:73], s[14:15]
	s_cbranch_execz .LBB0_306
	v_fma_f32 v41, v42, s99, v214
.LBB0_306:
	s_or_b64 exec, exec, s[72:73]
	v_or_b32_e32 v42, s1, v99
	s_and_b64 s[14:15], s[16:17], s[8:9]
	v_cmp_gt_i32_e32 vcc, s10, v42
	s_and_b64 s[14:15], s[14:15], vcc
	s_and_saveexec_b64 s[72:73], s[14:15]
	s_cbranch_execz .LBB0_308
	v_fma_f32 v40, v43, s99, v215
.LBB0_308:
	s_or_b64 exec, exec, s[72:73]
	v_or_b32_e32 v42, s1, v101
	s_and_b64 s[14:15], s[18:19], s[8:9]
	v_cmp_gt_i32_e32 vcc, s10, v42
	s_and_b64 s[14:15], s[14:15], vcc
	v_mov_b32_e32 v42, 0xf149f2ca
	v_mov_b32_e32 v43, 0xf149f2ca
	s_and_saveexec_b64 s[72:73], s[14:15]
	s_cbranch_execz .LBB0_310
	v_fma_f32 v43, v36, s99, v216
; __device__ __forceinline__ void attnA_item(const Frame& F, const Args& a, int item) {
;     ...
;     for (int ct = 0; ct < 12; ++ct)
; #pragma unroll
;         for (int j = 0; j < 4; ++j) { const int kk = 16 * ct + 4 * fq + j; const int rel = kk - 64 - qq; const int kp = kpw + kk;
;             const bool valid = (rel >= -64) && (rel <= 64) && (kp >= 0) && (kp < L);
;             const float bias = tab[valid ? rel + 64 : 64];
;             const float l = valid ? s[ct][j] * scale + bias : -1e30f; s[ct][j] = l; mx = fmaxf(mx, l); }
.LBB0_310:
	s_or_b64 exec, exec, s[72:73]
	v_or_b32_e32 v36, s1, v103
	s_and_b64 s[14:15], s[74:75], s[8:9]
	v_cmp_gt_i32_e32 vcc, s10, v36
	s_and_b64 s[14:15], s[14:15], vcc
	s_and_saveexec_b64 s[72:73], s[14:15]
	s_cbranch_execz .LBB0_312
	v_fma_f32 v42, v37, s99, v217
.LBB0_312:
	s_or_b64 exec, exec, s[72:73]
	v_or_b32_e32 v36, s1, v105
	s_and_b64 s[14:15], s[76:77], s[8:9]
	v_cmp_gt_i32_e32 vcc, s10, v36
	s_and_b64 s[14:15], s[14:15], vcc
	v_mov_b32_e32 v36, 0xf149f2ca
	v_mov_b32_e32 v37, 0xf149f2ca
	s_and_saveexec_b64 s[72:73], s[14:15]
	s_cbranch_execz .LBB0_314
	v_fma_f32 v37, v38, s99, v218
.LBB0_314:
	s_or_b64 exec, exec, s[72:73]
	v_or_b32_e32 v38, s1, v107
	s_and_b64 s[14:15], s[84:85], s[8:9]
	v_cmp_gt_i32_e32 vcc, s10, v38
	s_and_b64 s[14:15], s[14:15], vcc
	s_and_saveexec_b64 s[72:73], s[14:15]
	s_cbranch_execz .LBB0_316
	v_fma_f32 v36, v39, s99, v219
.LBB0_316:
	s_or_b64 exec, exec, s[72:73]
	v_or_b32_e32 v38, s1, v109
	s_and_b64 s[14:15], s[88:89], s[8:9]
	v_cmp_gt_i32_e32 vcc, s10, v38
	s_and_b64 s[14:15], s[14:15], vcc
	v_mov_b32_e32 v38, 0xf149f2ca
	v_mov_b32_e32 v39, 0xf149f2ca
	s_and_saveexec_b64 s[72:73], s[14:15]
	s_cbranch_execz .LBB0_318
	v_fma_f32 v39, v32, s99, v220
.LBB0_318:
	s_or_b64 exec, exec, s[72:73]
	v_or_b32_e32 v32, s1, v111
	s_and_b64 s[14:15], s[28:29], s[8:9]
	v_cmp_gt_i32_e32 vcc, s10, v32
	s_and_b64 s[14:15], s[14:15], vcc
	s_and_saveexec_b64 s[72:73], s[14:15]
	s_cbranch_execz .LBB0_320
	v_fma_f32 v38, v33, s99, v221
.LBB0_320:
	s_or_b64 exec, exec, s[72:73]
	v_or_b32_e32 v32, s1, v113
	s_and_b64 s[14:15], s[30:31], s[8:9]
	v_cmp_gt_i32_e32 vcc, s10, v32
	s_and_b64 s[14:15], s[14:15], vcc
	v_mov_b32_e32 v32, 0xf149f2ca
	v_mov_b32_e32 v33, 0xf149f2ca
	s_and_saveexec_b64 s[72:73], s[14:15]
	s_cbranch_execz .LBB0_322
	v_fma_f32 v33, v34, s99, v222
.LBB0_322:
	s_or_b64 exec, exec, s[72:73]
	v_or_b32_e32 v34, s1, v115
	s_and_b64 s[8:9], s[34:35], s[8:9]
	v_cmp_gt_i32_e32 vcc, s10, v34
	s_and_b64 s[14:15], s[8:9], vcc
	s_and_saveexec_b64 s[8:9], s[14:15]
	s_cbranch_execz .LBB0_324
	v_fma_f32 v32, v35, s99, v223
.LBB0_324:
	s_or_b64 exec, exec, s[8:9]
	v_or_b32_e32 v34, s12, v68
	v_cmp_gt_u32_e32 vcc, s10, v34
	v_mov_b32_e32 v35, 0xf149f2ca
	v_mov_b32_e32 v50, 0xf149f2ca
	s_and_saveexec_b64 s[8:9], vcc
	s_cbranch_execz .LBB0_326
	v_fma_f32 v50, v20, s99, v224
.LBB0_326:
	s_or_b64 exec, exec, s[8:9]
	v_add_u32_e32 v20, s1, v118
	v_cmp_gt_i32_e32 vcc, s10, v20
	s_and_saveexec_b64 s[8:9], vcc
	s_cbranch_execz .LBB0_328
	v_fma_f32 v35, v21, s99, v225
.LBB0_328:
	s_or_b64 exec, exec, s[8:9]
	v_add_u32_e32 v20, s1, v120
	v_cmp_gt_i32_e32 vcc, s10, v20
	v_mov_b32_e32 v20, 0xf149f2ca
	v_mov_b32_e32 v21, 0xf149f2ca
	s_and_saveexec_b64 s[8:9], vcc
	s_cbranch_execz .LBB0_330
	v_fma_f32 v21, v22, s99, v226
.LBB0_330:
	s_or_b64 exec, exec, s[8:9]
	v_add_u32_e32 v22, s1, v122
	v_cmp_gt_i32_e32 vcc, s10, v22
	s_and_saveexec_b64 s[8:9], vcc
	s_cbranch_execz .LBB0_332
	v_fma_f32 v20, v23, s99, v227
.LBB0_332:
	s_or_b64 exec, exec, s[8:9]
	v_add_u32_e32 v22, s1, v124
	v_cmp_gt_i32_e32 vcc, s10, v22
	v_mov_b32_e32 v22, 0xf149f2ca
	v_mov_b32_e32 v23, 0xf149f2ca
	s_and_saveexec_b64 s[8:9], vcc
	s_cbranch_execz .LBB0_334
	v_fma_f32 v23, v16, s99, v228
.LBB0_334:
	s_or_b64 exec, exec, s[8:9]
	v_add_u32_e32 v16, s1, v126
	v_cmp_gt_i32_e32 vcc, s10, v16
	s_and_saveexec_b64 s[8:9], vcc
	s_cbranch_execz .LBB0_336
	v_fma_f32 v22, v17, s99, v229
.LBB0_336:
	s_or_b64 exec, exec, s[8:9]
	v_add_u32_e32 v16, s1, v128
	v_cmp_gt_i32_e32 vcc, s10, v16
	v_mov_b32_e32 v16, 0xf149f2ca
	v_mov_b32_e32 v17, 0xf149f2ca
	s_and_saveexec_b64 s[8:9], vcc
	s_cbranch_execz .LBB0_338
	v_fma_f32 v17, v18, s99, v230
.LBB0_338:
	s_or_b64 exec, exec, s[8:9]
	v_add_u32_e32 v18, s1, v130
	v_cmp_gt_i32_e32 vcc, s10, v18
	s_and_saveexec_b64 s[8:9], vcc
	s_cbranch_execz .LBB0_340
	v_fma_f32 v16, v19, s99, v231
.LBB0_340:
	s_or_b64 exec, exec, s[8:9]
	v_add_u32_e32 v18, s1, v132
	v_cmp_gt_i32_e32 vcc, s10, v18
	v_mov_b32_e32 v18, 0xf149f2ca
	v_mov_b32_e32 v19, 0xf149f2ca
	s_and_saveexec_b64 s[8:9], vcc
	s_cbranch_execz .LBB0_342
	v_fma_f32 v19, v28, s99, v232
.LBB0_342:
	s_or_b64 exec, exec, s[8:9]
	v_add_u32_e32 v28, s1, v134
	v_cmp_gt_i32_e32 vcc, s10, v28
	s_and_saveexec_b64 s[8:9], vcc
	s_cbranch_execz .LBB0_344
	v_fma_f32 v18, v29, s99, v233
.LBB0_344:
	s_or_b64 exec, exec, s[8:9]
	v_add_u32_e32 v28, s1, v136
	v_cmp_gt_i32_e32 vcc, s10, v28
	v_mov_b32_e32 v28, 0xf149f2ca
	v_mov_b32_e32 v29, 0xf149f2ca
	s_and_saveexec_b64 s[8:9], vcc
	s_cbranch_execz .LBB0_346
	v_fma_f32 v29, v30, s99, v234
; __device__ __forceinline__ void attnA_item(const Frame& F, const Args& a, int item) {
;     ...
;     for (int ct = 0; ct < 12; ++ct)
; #pragma unroll
;         for (int j = 0; j < 4; ++j) { const int kk = 16 * ct + 4 * fq + j; const int rel = kk - 64 - qq; const int kp = kpw + kk;
;             const bool valid = (rel >= -64) && (rel <= 64) && (kp >= 0) && (kp < L);
;             const float bias = tab[valid ? rel + 64 : 64];
;             const float l = valid ? s[ct][j] * scale + bias : -1e30f; s[ct][j] = l; mx = fmaxf(mx, l); }
.LBB0_346:
	s_or_b64 exec, exec, s[8:9]
	v_add_u32_e32 v30, s1, v138
	v_cmp_gt_i32_e32 vcc, s10, v30
	s_and_saveexec_b64 s[8:9], vcc
	s_cbranch_execz .LBB0_348
	v_fma_f32 v28, v31, s99, v235
.LBB0_348:
	s_or_b64 exec, exec, s[8:9]
	v_add_u32_e32 v30, s1, v140
	v_cmp_gt_i32_e32 vcc, s10, v30
	v_mov_b32_e32 v30, 0xf149f2ca
	v_mov_b32_e32 v31, 0xf149f2ca
	s_and_saveexec_b64 s[8:9], vcc
	s_cbranch_execz .LBB0_350
	v_fma_f32 v31, v24, s99, v236
.LBB0_350:
	s_or_b64 exec, exec, s[8:9]
	v_add_u32_e32 v24, s1, v142
	v_cmp_gt_i32_e32 vcc, s10, v24
	s_and_saveexec_b64 s[8:9], vcc
	s_cbranch_execz .LBB0_352
	v_fma_f32 v30, v25, s99, v237
.LBB0_352:
	s_or_b64 exec, exec, s[8:9]
	v_add_u32_e32 v24, s1, v145
	v_cmp_gt_i32_e32 vcc, s10, v24
	v_mov_b32_e32 v24, 0xf149f2ca
	v_mov_b32_e32 v25, 0xf149f2ca
	s_and_saveexec_b64 s[8:9], vcc
	s_cbranch_execz .LBB0_354
	v_fma_f32 v25, v26, s99, v238
.LBB0_354:
	s_or_b64 exec, exec, s[8:9]
	v_add_u32_e32 v26, s1, v147
	v_cmp_gt_i32_e32 vcc, s10, v26
	s_and_saveexec_b64 s[8:9], vcc
	s_cbranch_execz .LBB0_356
	v_fma_f32 v24, v27, s99, v239
.LBB0_356:
	s_or_b64 exec, exec, s[8:9]
	v_add_u32_e32 v26, s1, v149
	v_cmp_gt_i32_e32 vcc, s10, v26
	s_and_b64 s[12:13], s[36:37], vcc
	v_mov_b32_e32 v26, 0xf149f2ca
	v_mov_b32_e32 v27, 0xf149f2ca
	s_and_saveexec_b64 s[8:9], s[12:13]
	s_cbranch_execz .LBB0_358
	v_fma_f32 v27, v12, s99, v240
.LBB0_358:
	s_or_b64 exec, exec, s[8:9]
	v_add_u32_e32 v12, s1, v151
	v_cmp_gt_i32_e32 vcc, s10, v12
	s_and_b64 s[12:13], s[38:39], vcc
	s_and_saveexec_b64 s[8:9], s[12:13]
	s_cbranch_execz .LBB0_360
	v_fma_f32 v26, v13, s99, v241
.LBB0_360:
	s_or_b64 exec, exec, s[8:9]
	v_add_u32_e32 v12, s1, v153
	v_cmp_gt_i32_e32 vcc, s10, v12
	s_and_b64 s[12:13], s[40:41], vcc
	v_mov_b32_e32 v12, 0xf149f2ca
	v_mov_b32_e32 v13, 0xf149f2ca
	s_and_saveexec_b64 s[8:9], s[12:13]
	s_cbranch_execz .LBB0_362
	v_fma_f32 v13, v14, s99, v244
.LBB0_362:
	s_or_b64 exec, exec, s[8:9]
	v_add_u32_e32 v14, s1, v155
	v_cmp_gt_i32_e32 vcc, s10, v14
	s_and_b64 s[12:13], s[42:43], vcc
	s_and_saveexec_b64 s[8:9], s[12:13]
	s_cbranch_execz .LBB0_364
	v_fma_f32 v12, v15, s99, v245
.LBB0_364:
	s_or_b64 exec, exec, s[8:9]
	v_add_u32_e32 v14, s1, v157
	v_cmp_gt_i32_e32 vcc, s10, v14
	s_and_b64 s[12:13], s[44:45], vcc
	v_mov_b32_e32 v14, 0xf149f2ca
	v_mov_b32_e32 v15, 0xf149f2ca
	s_and_saveexec_b64 s[8:9], s[12:13]
	s_cbranch_execz .LBB0_366
	v_fma_f32 v15, v8, s99, v246
.LBB0_366:
	s_or_b64 exec, exec, s[8:9]
	v_add_u32_e32 v8, s1, v159
	v_cmp_gt_i32_e32 vcc, s10, v8
	s_and_b64 s[12:13], s[46:47], vcc
	s_and_saveexec_b64 s[8:9], s[12:13]
	s_cbranch_execz .LBB0_368
	v_fma_f32 v14, v9, s99, v247
.LBB0_368:
	s_or_b64 exec, exec, s[8:9]
	v_add_u32_e32 v8, s1, v161
	v_cmp_gt_i32_e32 vcc, s10, v8
	s_and_b64 s[12:13], s[48:49], vcc
	v_mov_b32_e32 v8, 0xf149f2ca
	v_mov_b32_e32 v9, 0xf149f2ca
	s_and_saveexec_b64 s[8:9], s[12:13]
	s_cbranch_execz .LBB0_370
	v_fma_f32 v9, v10, s99, v248
.LBB0_370:
	s_or_b64 exec, exec, s[8:9]
	v_add_u32_e32 v10, s1, v163
	v_cmp_gt_i32_e32 vcc, s10, v10
	s_and_b64 s[12:13], s[50:51], vcc
	s_and_saveexec_b64 s[8:9], s[12:13]
	s_cbranch_execz .LBB0_372
	v_fma_f32 v8, v11, s99, v249
.LBB0_372:
	s_or_b64 exec, exec, s[8:9]
	v_add_u32_e32 v10, s1, v165
	v_cmp_gt_i32_e32 vcc, s10, v10
	s_and_b64 s[12:13], s[52:53], vcc
	v_mov_b32_e32 v10, 0xf149f2ca
	v_mov_b32_e32 v11, 0xf149f2ca
	s_and_saveexec_b64 s[8:9], s[12:13]
	s_cbranch_execz .LBB0_374
	v_fma_f32 v11, v4, s99, v250
.LBB0_374:
	s_or_b64 exec, exec, s[8:9]
	v_add_u32_e32 v4, s1, v167
	v_cmp_gt_i32_e32 vcc, s10, v4
	s_and_b64 s[12:13], s[54:55], vcc
	s_and_saveexec_b64 s[8:9], s[12:13]
	s_cbranch_execz .LBB0_376
	v_fma_f32 v10, v5, s99, v251
.LBB0_376:
	s_or_b64 exec, exec, s[8:9]
	v_add_u32_e32 v4, s1, v169
	v_cmp_gt_i32_e32 vcc, s10, v4
	s_and_b64 s[12:13], s[56:57], vcc
	v_mov_b32_e32 v4, 0xf149f2ca
	v_mov_b32_e32 v5, 0xf149f2ca
	s_and_saveexec_b64 s[8:9], s[12:13]
	s_cbranch_execz .LBB0_378
	v_fma_f32 v5, v6, s99, v252
.LBB0_378:
	s_or_b64 exec, exec, s[8:9]
	v_add_u32_e32 v6, s1, v171
	v_cmp_gt_i32_e32 vcc, s10, v6
	s_and_b64 s[12:13], s[58:59], vcc
	s_and_saveexec_b64 s[8:9], s[12:13]
	s_cbranch_execz .LBB0_380
	v_fma_f32 v4, v7, s99, v253
.LBB0_380:
	s_or_b64 exec, exec, s[8:9]
	v_add_u32_e32 v6, s1, v173
	v_cmp_gt_i32_e32 vcc, s10, v6
	s_and_b64 s[12:13], s[60:61], vcc
	v_mov_b32_e32 v6, 0xf149f2ca
	v_mov_b32_e32 v7, 0xf149f2ca
	s_and_saveexec_b64 s[8:9], s[12:13]
	s_cbranch_execz .LBB0_382
	v_fma_f32 v7, v0, s99, v254
.LBB0_382:
	s_or_b64 exec, exec, s[8:9]
	v_add_u32_e32 v0, s1, v175
	v_cmp_gt_i32_e32 vcc, s10, v0
	s_and_b64 s[12:13], s[62:63], vcc
	s_and_saveexec_b64 s[8:9], s[12:13]
	s_cbranch_execz .LBB0_384
	v_fma_f32 v6, v1, s99, v255

; #define LAS __attribute__((address_space(3)))
; template <int NCT>
; __device__ __forceinline__ void qk_accum(f32x4 (&s)[NCT], const LAS unsigned char* Kt, int key_row0, const bf16x8 (&qf)[4], int fr, int fq) {
; #pragma unroll
;     for (int ct = 0; ct < NCT; ++ct)
; #pragma unroll
;         for (int ks = 0; ks < 4; ++ks) { const bf16x8 kf = *(const LAS bf16x8*)(Kt + (key_row0 + 16 * ct + fr) * AT_PITCH + 64 * ks + 16 * fq);
;             s[ct] = __builtin_amdgcn_mfma_f32_16x16x32_bf16(kf, qf[ks], s[ct], 0, 0, 0); if (ks == 3 && (ct & 1)) asm volatile("" ::: "memory"); }
; }
; __device__ __forceinline__ void attnA_item(const Frame& F, const Args& a, int item) {
;     ...
;     const int qq = 16 * (F.wave & 3) + fr;
;     const int qpos = (n0 + hb) * 64 + qq;
;     const size_t qrow = rowbase + (size_t)qpos * d + r;
;     bf16x8 qf[4];
; #pragma unroll
;     for (int ks = 0; ks < 4; ++ks) qf[ks] = *(const bf16x8*)(proj + qrow * NIN + C_Q + h * 128 + 32 * ks + 8 * fq);
;     __syncthreads();
;     f32x4 s[12];
; #pragma unroll
;     for (int ct = 0; ct < 12; ++ct) s[ct] = (f32x4){0.f, 0.f, 0.f, 0.f};
;     qk_accum<12>(s, R0, 64 * hb, qf, fr, fq);
.LBB0_468:
	s_or_b64 exec, exec, s[72:73]
	s_add_i32 s12, s12, s95
	v_or_b32_e32 v66, s12, v86
	v_lshlrev_b64 v[0:1], s11, v[66:67]
	v_lshl_add_u64 v[60:61], v[0:1], 0, s[8:9]
	v_mov_b64_e32 v[0:1], s[96:97]
	v_mad_u64_u32 v[0:1], s[8:9], v60, s93, v[0:1]
	v_mov_b32_e32 v2, v1
	v_mad_u64_u32 v[2:3], s[8:9], v61, s93, v[2:3]
	v_mov_b32_e32 v1, v2
	v_lshl_add_u64 v[0:1], s[2:3], 1, v[0:1]
	v_mov_b32_e32 v71, v67
	v_lshl_add_u64 v[0:1], v[0:1], 0, v[70:71]
	global_load_dwordx4 v[56:59], v[0:1], off
	global_load_dwordx4 v[52:55], v[0:1], off offset:64
	global_load_dwordx4 v[48:51], v[0:1], off offset:128
	s_nop 0
	global_load_dwordx4 v[0:3], v[0:1], off offset:192
	s_waitcnt lgkmcnt(0)
	s_barrier
	s_sub_i32 s3, s12, 64
	s_cmp_lg_u32 s12, 0
	v_readlane_b32 s14, v242, 44
	s_cselect_b64 s[8:9], -1, 0
	v_readlane_b32 s15, v242, 45
	s_and_b64 s[14:15], s[14:15], s[8:9]
	ds_read_b128 v[208:211], v196
	ds_read_b128 v[212:215], v196 offset:64
	ds_read_b128 v[216:219], v196 offset:128
	ds_read_b128 v[220:223], v196 offset:192
	ds_read_b128 v[224:227], v196 offset:4352
	ds_read_b128 v[228:231], v196 offset:4416
	ds_read_b128 v[232:235], v196 offset:4480
	ds_read_b128 v[236:239], v196 offset:4544
	ds_read_b128 v[244:247], v196 offset:8704
	ds_read_b128 v[248:251], v196 offset:8768
	ds_read_b128 v[252:255], v196 offset:8832
	s_waitcnt vmcnt(0)
	s_waitcnt lgkmcnt(10)
	v_mfma_f32_16x16x32_bf16 v[4:7], v[208:211], v[56:59], 0
	ds_read_b128 v[208:211], v196 offset:8896
	s_waitcnt lgkmcnt(10)
	v_mfma_f32_16x16x32_bf16 v[4:7], v[212:215], v[52:55], v[4:7]
	ds_read_b128 v[212:215], v196 offset:13056
	s_waitcnt lgkmcnt(10)
	v_mfma_f32_16x16x32_bf16 v[4:7], v[216:219], v[48:51], v[4:7]
	ds_read_b128 v[216:219], v196 offset:13120
	s_waitcnt lgkmcnt(10)
	v_mfma_f32_16x16x32_bf16 v[44:47], v[220:223], v[0:3], v[4:7]
	ds_read_b128 v[220:223], v196 offset:13184
	s_waitcnt lgkmcnt(10)
	v_mfma_f32_16x16x32_bf16 v[4:7], v[224:227], v[56:59], 0
	ds_read_b128 v[224:227], v196 offset:13248
	s_waitcnt lgkmcnt(10)
	v_mfma_f32_16x16x32_bf16 v[4:7], v[228:231], v[52:55], v[4:7]
	ds_read_b128 v[228:231], v196 offset:17408
	s_waitcnt lgkmcnt(10)
	v_mfma_f32_16x16x32_bf16 v[4:7], v[232:235], v[48:51], v[4:7]
	ds_read_b128 v[232:235], v196 offset:17472
	s_waitcnt lgkmcnt(10)
	v_mfma_f32_16x16x32_bf16 v[40:43], v[236:239], v[0:3], v[4:7]
	ds_read_b128 v[236:239], v196 offset:17536
	s_waitcnt lgkmcnt(10)
	v_mfma_f32_16x16x32_bf16 v[4:7], v[244:247], v[56:59], 0
	ds_read_b128 v[244:247], v196 offset:17600
	s_waitcnt lgkmcnt(10)
	v_mfma_f32_16x16x32_bf16 v[4:7], v[248:251], v[52:55], v[4:7]
	ds_read_b128 v[248:251], v196 offset:21760
	s_waitcnt lgkmcnt(10)
	v_mfma_f32_16x16x32_bf16 v[4:7], v[252:255], v[48:51], v[4:7]
	ds_read_b128 v[252:255], v196 offset:21824
	s_waitcnt lgkmcnt(10)
	v_mfma_f32_16x16x32_bf16 v[36:39], v[208:211], v[0:3], v[4:7]
	ds_read_b128 v[208:211], v196 offset:21888
	s_waitcnt lgkmcnt(10)
	v_mfma_f32_16x16x32_bf16 v[4:7], v[212:215], v[56:59], 0
	ds_read_b128 v[212:215], v196 offset:21952
	s_waitcnt lgkmcnt(10)
	v_mfma_f32_16x16x32_bf16 v[4:7], v[216:219], v[52:55], v[4:7]
	ds_read_b128 v[216:219], v196 offset:26112
	s_waitcnt lgkmcnt(10)
	v_mfma_f32_16x16x32_bf16 v[4:7], v[220:223], v[48:51], v[4:7]
	ds_read_b128 v[220:223], v196 offset:26176
	s_waitcnt lgkmcnt(10)
	v_mfma_f32_16x16x32_bf16 v[32:35], v[224:227], v[0:3], v[4:7]
	ds_read_b128 v[224:227], v196 offset:26240
	s_waitcnt lgkmcnt(10)
	v_mfma_f32_16x16x32_bf16 v[4:7], v[228:231], v[56:59], 0
	ds_read_b128 v[228:231], v196 offset:26304
	s_waitcnt lgkmcnt(10)
	v_mfma_f32_16x16x32_bf16 v[4:7], v[232:235], v[52:55], v[4:7]
	ds_read_b128 v[232:235], v196 offset:30464
	s_waitcnt lgkmcnt(10)
	v_mfma_f32_16x16x32_bf16 v[4:7], v[236:239], v[48:51], v[4:7]
	ds_read_b128 v[236:239], v196 offset:30528
	s_waitcnt lgkmcnt(10)
	v_mfma_f32_16x16x32_bf16 v[20:23], v[244:247], v[0:3], v[4:7]
	ds_read_b128 v[244:247], v196 offset:30592
	s_waitcnt lgkmcnt(10)
	v_mfma_f32_16x16x32_bf16 v[4:7], v[248:251], v[56:59], 0
	ds_read_b128 v[248:251], v196 offset:30656
	s_waitcnt lgkmcnt(10)
	v_mfma_f32_16x16x32_bf16 v[4:7], v[252:255], v[52:55], v[4:7]
	ds_read_b128 v[252:255], v196 offset:34816
	s_waitcnt lgkmcnt(10)
	v_mfma_f32_16x16x32_bf16 v[4:7], v[208:211], v[48:51], v[4:7]
	ds_read_b128 v[208:211], v196 offset:34880
	s_waitcnt lgkmcnt(10)
	v_mfma_f32_16x16x32_bf16 v[16:19], v[212:215], v[0:3], v[4:7]
	ds_read_b128 v[212:215], v196 offset:34944
	s_waitcnt lgkmcnt(10)
	v_mfma_f32_16x16x32_bf16 v[4:7], v[216:219], v[56:59], 0
	ds_read_b128 v[216:219], v196 offset:35008
	s_waitcnt lgkmcnt(10)
	v_mfma_f32_16x16x32_bf16 v[4:7], v[220:223], v[52:55], v[4:7]
	ds_read_b128 v[220:223], v196 offset:39168
	s_waitcnt lgkmcnt(10)
	v_mfma_f32_16x16x32_bf16 v[4:7], v[224:227], v[48:51], v[4:7]
	ds_read_b128 v[224:227], v196 offset:39232
	s_waitcnt lgkmcnt(10)
	v_mfma_f32_16x16x32_bf16 v[28:31], v[228:231], v[0:3], v[4:7]
	ds_read_b128 v[228:231], v196 offset:39296
	s_waitcnt lgkmcnt(10)
	v_mfma_f32_16x16x32_bf16 v[4:7], v[232:235], v[56:59], 0
	ds_read_b128 v[232:235], v196 offset:39360
	s_waitcnt lgkmcnt(10)
	v_mfma_f32_16x16x32_bf16 v[4:7], v[236:239], v[52:55], v[4:7]
	ds_read_b128 v[236:239], v196 offset:43584
	s_waitcnt lgkmcnt(10)
	v_mfma_f32_16x16x32_bf16 v[4:7], v[244:247], v[48:51], v[4:7]
	ds_read_b128 v[244:247], v196 offset:43520
	s_waitcnt lgkmcnt(10)
	v_mfma_f32_16x16x32_bf16 v[24:27], v[248:251], v[0:3], v[4:7]
	ds_read_b128 v[248:251], v196 offset:43648
	s_waitcnt lgkmcnt(10)
	v_mfma_f32_16x16x32_bf16 v[4:7], v[252:255], v[56:59], 0
	ds_read_b128 v[252:255], v196 offset:43712
	s_waitcnt lgkmcnt(10)
; #define LAS __attribute__((address_space(3)))
; template <int NCT>
; __device__ __forceinline__ void qk_accum(f32x4 (&s)[NCT], const LAS unsigned char* Kt, int key_row0, const bf16x8 (&qf)[4], int fr, int fq) {
; #pragma unroll
;     for (int ct = 0; ct < NCT; ++ct)
; #pragma unroll
;         for (int ks = 0; ks < 4; ++ks) { const bf16x8 kf = *(const LAS bf16x8*)(Kt + (key_row0 + 16 * ct + fr) * AT_PITCH + 64 * ks + 16 * fq);
;             s[ct] = __builtin_amdgcn_mfma_f32_16x16x32_bf16(kf, qf[ks], s[ct], 0, 0, 0); if (ks == 3 && (ct & 1)) asm volatile("" ::: "memory"); }
; }
; __device__ __forceinline__ void attnA_item(const Frame& F, const Args& a, int item) {
;     ...
;     for (int ct = 0; ct < 12; ++ct)
; #pragma unroll
;         for (int j = 0; j < 4; ++j) { const int kk = 16 * ct + 4 * fq + j; const int rel = kk - 64 - qq; const int kp = kpw + kk;
;             const bool valid = (rel >= -64) && (rel <= 64) && (kp >= 0) && (kp < L);
;             const float bias = tab[valid ? rel + 64 : 64];
;             const float l = valid ? s[ct][j] * scale + bias : -1e30f; s[ct][j] = l; mx = fmaxf(mx, l); }
	v_mfma_f32_16x16x32_bf16 v[4:7], v[208:211], v[52:55], v[4:7]
	ds_read_b128 v[208:211], v196 offset:47872
	s_waitcnt lgkmcnt(10)
	v_mfma_f32_16x16x32_bf16 v[4:7], v[212:215], v[48:51], v[4:7]
	ds_read_b128 v[212:215], v196 offset:47936
	s_waitcnt lgkmcnt(10)
	v_mfma_f32_16x16x32_bf16 v[12:15], v[216:219], v[0:3], v[4:7]
	ds_read_b128 v[216:219], v196 offset:48000
	s_waitcnt lgkmcnt(10)
	v_mfma_f32_16x16x32_bf16 v[4:7], v[220:223], v[56:59], 0
	ds_read_b128 v[220:223], v196 offset:48064
	s_waitcnt lgkmcnt(10)
	v_mfma_f32_16x16x32_bf16 v[4:7], v[224:227], v[52:55], v[4:7]
	s_waitcnt lgkmcnt(9)
	v_mfma_f32_16x16x32_bf16 v[4:7], v[228:231], v[48:51], v[4:7]
	s_waitcnt lgkmcnt(8)
	v_mfma_f32_16x16x32_bf16 v[8:11], v[232:235], v[0:3], v[4:7]
	s_waitcnt lgkmcnt(6)
	v_mfma_f32_16x16x32_bf16 v[4:7], v[244:247], v[56:59], 0
	s_waitcnt lgkmcnt(7)
	v_mfma_f32_16x16x32_bf16 v[4:7], v[236:239], v[52:55], v[4:7]
	s_waitcnt lgkmcnt(5)
	v_mfma_f32_16x16x32_bf16 v[4:7], v[248:251], v[48:51], v[4:7]
	s_waitcnt lgkmcnt(4)
	v_mfma_f32_16x16x32_bf16 v[4:7], v[252:255], v[0:3], v[4:7]
	s_waitcnt lgkmcnt(3)
	v_mfma_f32_16x16x32_bf16 v[56:59], v[208:211], v[56:59], 0
	s_waitcnt lgkmcnt(2)
	v_mfma_f32_16x16x32_bf16 v[52:55], v[212:215], v[52:55], v[56:59]
	s_waitcnt lgkmcnt(1)
	v_mfma_f32_16x16x32_bf16 v[48:51], v[216:219], v[48:51], v[52:55]
	s_waitcnt lgkmcnt(0)
	v_mfma_f32_16x16x32_bf16 v[0:3], v[220:223], v[0:3], v[48:51]
	s_nop 2
	s_mov_b32 s99, 0x3db504f3
	ds_read_b32 v208, v87
	ds_read_b32 v209, v89
	ds_read_b32 v210, v91
	ds_read_b32 v211, v93
	ds_read_b32 v212, v95
	ds_read_b32 v213, v97
	ds_read_b32 v214, v99
	ds_read_b32 v215, v101
	ds_read_b32 v216, v103
	ds_read_b32 v217, v105
	ds_read_b32 v218, v107
	ds_read_b32 v219, v109
	ds_read_b32 v220, v111
	ds_read_b32 v221, v113
	ds_read_b32 v222, v115
	ds_read_b32 v223, v117
	ds_read_b32 v224, v118
	ds_read_b32 v225, v120
	ds_read_b32 v226, v122
	ds_read_b32 v227, v124
	ds_read_b32 v228, v126
	ds_read_b32 v229, v128
	ds_read_b32 v230, v130
	ds_read_b32 v231, v132
	ds_read_b32 v232, v134
	ds_read_b32 v233, v136
	ds_read_b32 v234, v138
	ds_read_b32 v235, v140
	ds_read_b32 v236, v142
	ds_read_b32 v237, v145
	ds_read_b32 v238, v147
	ds_read_b32 v239, v149
	ds_read_b32 v240, v151
	ds_read_b32 v241, v153
	ds_read_b32 v244, v155
	ds_read_b32 v245, v157
	ds_read_b32 v246, v159
	ds_read_b32 v247, v161
	ds_read_b32 v248, v163
	ds_read_b32 v249, v165
	ds_read_b32 v250, v167
	ds_read_b32 v251, v169
	ds_read_b32 v252, v171
	ds_read_b32 v253, v173
	ds_read_b32 v254, v175
	ds_read_b32 v255, v177
	s_waitcnt lgkmcnt(0)
	v_or_b32_e32 v48, s3, v68
	v_cmp_gt_i32_e32 vcc, s10, v48
	s_and_b64 s[14:15], s[14:15], vcc
	v_mov_b32_e32 v48, 0xf149f2ca
	v_mov_b32_e32 v49, 0xf149f2ca
	s_and_saveexec_b64 s[72:73], s[14:15]
	s_cbranch_execz .LBB0_470
	v_fma_f32 v49, v44, s99, v208
.LBB0_470:
	s_or_b64 exec, exec, s[72:73]
	v_readlane_b32 s14, v242, 46
	v_or_b32_e32 v44, s3, v88
	v_readlane_b32 s15, v242, 47
	s_and_b64 s[14:15], s[14:15], s[8:9]
	v_cmp_gt_i32_e32 vcc, s10, v44
	s_and_b64 s[14:15], s[14:15], vcc
	s_and_saveexec_b64 s[72:73], s[14:15]
	s_cbranch_execz .LBB0_472
	v_fma_f32 v48, v45, s99, v209
.LBB0_472:
	s_or_b64 exec, exec, s[72:73]
	v_readlane_b32 s14, v242, 48
	v_or_b32_e32 v44, s3, v90
	v_readlane_b32 s15, v242, 49
	s_and_b64 s[14:15], s[14:15], s[8:9]
	v_cmp_gt_i32_e32 vcc, s10, v44
	s_and_b64 s[14:15], s[14:15], vcc
	v_mov_b32_e32 v44, 0xf149f2ca
	v_mov_b32_e32 v45, 0xf149f2ca
	s_and_saveexec_b64 s[72:73], s[14:15]
	s_cbranch_execz .LBB0_474
	v_fma_f32 v45, v46, s99, v210
.LBB0_474:
	s_or_b64 exec, exec, s[72:73]
	v_readlane_b32 s14, v242, 50
	v_or_b32_e32 v46, s3, v92
	v_readlane_b32 s15, v242, 51
	s_and_b64 s[14:15], s[14:15], s[8:9]
	v_cmp_gt_i32_e32 vcc, s10, v46
	s_and_b64 s[14:15], s[14:15], vcc
	s_and_saveexec_b64 s[72:73], s[14:15]
	s_cbranch_execz .LBB0_476
	v_fma_f32 v44, v47, s99, v211
; __device__ __forceinline__ void attnA_item(const Frame& F, const Args& a, int item) {
;     ...
;     for (int ct = 0; ct < 12; ++ct)
; #pragma unroll
;         for (int j = 0; j < 4; ++j) { const int kk = 16 * ct + 4 * fq + j; const int rel = kk - 64 - qq; const int kp = kpw + kk;
;             const bool valid = (rel >= -64) && (rel <= 64) && (kp >= 0) && (kp < L);
;             const float bias = tab[valid ? rel + 64 : 64];
;             const float l = valid ? s[ct][j] * scale + bias : -1e30f; s[ct][j] = l; mx = fmaxf(mx, l); }
.LBB0_476:
	s_or_b64 exec, exec, s[72:73]
	v_readlane_b32 s14, v242, 52
	v_or_b32_e32 v46, s3, v94
	v_readlane_b32 s15, v242, 53
	s_and_b64 s[14:15], s[14:15], s[8:9]
	v_cmp_gt_i32_e32 vcc, s10, v46
	s_and_b64 s[14:15], s[14:15], vcc
	v_mov_b32_e32 v46, 0xf149f2ca
	v_mov_b32_e32 v47, 0xf149f2ca
	s_and_saveexec_b64 s[72:73], s[14:15]
	s_cbranch_execz .LBB0_478
	v_fma_f32 v47, v40, s99, v212
.LBB0_478:
	s_or_b64 exec, exec, s[72:73]
	v_readlane_b32 s14, v242, 54
	v_or_b32_e32 v40, s3, v96
	v_readlane_b32 s15, v242, 55
	s_and_b64 s[14:15], s[14:15], s[8:9]
	v_cmp_gt_i32_e32 vcc, s10, v40
	s_and_b64 s[14:15], s[14:15], vcc
	s_and_saveexec_b64 s[72:73], s[14:15]
	s_cbranch_execz .LBB0_480
	v_fma_f32 v46, v41, s99, v213
.LBB0_480:
	s_or_b64 exec, exec, s[72:73]
	v_readlane_b32 s14, v242, 56
	v_or_b32_e32 v40, s3, v98
	v_readlane_b32 s15, v242, 57
	s_and_b64 s[14:15], s[14:15], s[8:9]
	v_cmp_gt_i32_e32 vcc, s10, v40
	s_and_b64 s[14:15], s[14:15], vcc
	v_mov_b32_e32 v40, 0xf149f2ca
	v_mov_b32_e32 v41, 0xf149f2ca
	s_and_saveexec_b64 s[72:73], s[14:15]
	s_cbranch_execz .LBB0_482
	v_fma_f32 v41, v42, s99, v214
.LBB0_482:
	s_or_b64 exec, exec, s[72:73]
	v_or_b32_e32 v42, s3, v100
	s_and_b64 s[14:15], s[16:17], s[8:9]
	v_cmp_gt_i32_e32 vcc, s10, v42
	s_and_b64 s[14:15], s[14:15], vcc
	s_and_saveexec_b64 s[72:73], s[14:15]
	s_cbranch_execz .LBB0_484
	v_fma_f32 v40, v43, s99, v215
.LBB0_484:
	s_or_b64 exec, exec, s[72:73]
	v_or_b32_e32 v42, s3, v102
	s_and_b64 s[14:15], s[18:19], s[8:9]
	v_cmp_gt_i32_e32 vcc, s10, v42
	s_and_b64 s[14:15], s[14:15], vcc
	v_mov_b32_e32 v42, 0xf149f2ca
	v_mov_b32_e32 v43, 0xf149f2ca
	s_and_saveexec_b64 s[72:73], s[14:15]
	s_cbranch_execz .LBB0_486
	v_fma_f32 v43, v36, s99, v216
.LBB0_486:
	s_or_b64 exec, exec, s[72:73]
	v_or_b32_e32 v36, s3, v104
	s_and_b64 s[14:15], s[74:75], s[8:9]
	v_cmp_gt_i32_e32 vcc, s10, v36
	s_and_b64 s[14:15], s[14:15], vcc
	s_and_saveexec_b64 s[72:73], s[14:15]
	s_cbranch_execz .LBB0_488
	v_fma_f32 v42, v37, s99, v217
.LBB0_488:
	s_or_b64 exec, exec, s[72:73]
	v_or_b32_e32 v36, s3, v106
	s_and_b64 s[14:15], s[76:77], s[8:9]
	v_cmp_gt_i32_e32 vcc, s10, v36
	s_and_b64 s[14:15], s[14:15], vcc
	v_mov_b32_e32 v36, 0xf149f2ca
	v_mov_b32_e32 v37, 0xf149f2ca
	s_and_saveexec_b64 s[72:73], s[14:15]
	s_cbranch_execz .LBB0_490
	v_fma_f32 v37, v38, s99, v218
.LBB0_490:
	s_or_b64 exec, exec, s[72:73]
	v_or_b32_e32 v38, s3, v108
	s_and_b64 s[14:15], s[84:85], s[8:9]
	v_cmp_gt_i32_e32 vcc, s10, v38
	s_and_b64 s[14:15], s[14:15], vcc
	s_and_saveexec_b64 s[72:73], s[14:15]
	s_cbranch_execz .LBB0_492
	v_fma_f32 v36, v39, s99, v219
.LBB0_492:
	s_or_b64 exec, exec, s[72:73]
	v_or_b32_e32 v38, s3, v110
	s_and_b64 s[14:15], s[88:89], s[8:9]
	v_cmp_gt_i32_e32 vcc, s10, v38
	s_and_b64 s[14:15], s[14:15], vcc
	v_mov_b32_e32 v38, 0xf149f2ca
	v_mov_b32_e32 v39, 0xf149f2ca
	s_and_saveexec_b64 s[72:73], s[14:15]
	s_cbranch_execz .LBB0_494
	v_fma_f32 v39, v32, s99, v220
.LBB0_494:
	s_or_b64 exec, exec, s[72:73]
	v_or_b32_e32 v32, s3, v112
	s_and_b64 s[14:15], s[28:29], s[8:9]
	v_cmp_gt_i32_e32 vcc, s10, v32
	s_and_b64 s[14:15], s[14:15], vcc
	s_and_saveexec_b64 s[72:73], s[14:15]
	s_cbranch_execz .LBB0_496
	v_fma_f32 v38, v33, s99, v221
.LBB0_496:
	s_or_b64 exec, exec, s[72:73]
	v_or_b32_e32 v32, s3, v114
	s_and_b64 s[14:15], s[30:31], s[8:9]
	v_cmp_gt_i32_e32 vcc, s10, v32
	s_and_b64 s[14:15], s[14:15], vcc
	v_mov_b32_e32 v32, 0xf149f2ca
	v_mov_b32_e32 v33, 0xf149f2ca
	s_and_saveexec_b64 s[72:73], s[14:15]
	s_cbranch_execz .LBB0_498
	v_fma_f32 v33, v34, s99, v222
.LBB0_498:
	s_or_b64 exec, exec, s[72:73]
	v_or_b32_e32 v34, s3, v116
	s_and_b64 s[8:9], s[34:35], s[8:9]
	v_cmp_gt_i32_e32 vcc, s10, v34
	s_and_b64 s[14:15], s[8:9], vcc
	s_and_saveexec_b64 s[8:9], s[14:15]
	s_cbranch_execz .LBB0_500
	v_fma_f32 v32, v35, s99, v223

; __device__ __forceinline__ void attnA_item(const Frame& F, const Args& a, int item) {
;     ...
;     for (int ct = 0; ct < 12; ++ct)
; #pragma unroll
;         for (int j = 0; j < 4; ++j) { const int kk = 16 * ct + 4 * fq + j; const int rel = kk - 64 - qq; const int kp = kpw + kk;
;             const bool valid = (rel >= -64) && (rel <= 64) && (kp >= 0) && (kp < L);
;             const float bias = tab[valid ? rel + 64 : 64];
;             const float l = valid ? s[ct][j] * scale + bias : -1e30f; s[ct][j] = l; mx = fmaxf(mx, l); }
.LBB0_502:
	s_or_b64 exec, exec, s[8:9]
	v_add_u32_e32 v20, s3, v119
	v_cmp_gt_i32_e32 vcc, s10, v20
	s_and_saveexec_b64 s[8:9], vcc
	s_cbranch_execz .LBB0_504
	v_fma_f32 v35, v21, s99, v225
.LBB0_504:
	s_or_b64 exec, exec, s[8:9]
	v_add_u32_e32 v20, s3, v121
	v_cmp_gt_i32_e32 vcc, s10, v20
	v_mov_b32_e32 v20, 0xf149f2ca
	v_mov_b32_e32 v21, 0xf149f2ca
	s_and_saveexec_b64 s[8:9], vcc
	s_cbranch_execz .LBB0_506
	v_fma_f32 v21, v22, s99, v226
.LBB0_506:
	s_or_b64 exec, exec, s[8:9]
	v_add_u32_e32 v22, s3, v123
	v_cmp_gt_i32_e32 vcc, s10, v22
	s_and_saveexec_b64 s[8:9], vcc
	s_cbranch_execz .LBB0_508
	v_fma_f32 v20, v23, s99, v227
.LBB0_508:
	s_or_b64 exec, exec, s[8:9]
	v_add_u32_e32 v22, s3, v125
	v_cmp_gt_i32_e32 vcc, s10, v22
	v_mov_b32_e32 v22, 0xf149f2ca
	v_mov_b32_e32 v23, 0xf149f2ca
	s_and_saveexec_b64 s[8:9], vcc
	s_cbranch_execz .LBB0_510
	v_fma_f32 v23, v16, s99, v228
.LBB0_510:
	s_or_b64 exec, exec, s[8:9]
	v_add_u32_e32 v16, s3, v127
	v_cmp_gt_i32_e32 vcc, s10, v16
	s_and_saveexec_b64 s[8:9], vcc
	s_cbranch_execz .LBB0_512
	v_fma_f32 v22, v17, s99, v229
.LBB0_512:
	s_or_b64 exec, exec, s[8:9]
	v_add_u32_e32 v16, s3, v129
	v_cmp_gt_i32_e32 vcc, s10, v16
	v_mov_b32_e32 v16, 0xf149f2ca
	v_mov_b32_e32 v17, 0xf149f2ca
	s_and_saveexec_b64 s[8:9], vcc
	s_cbranch_execz .LBB0_514
	v_fma_f32 v17, v18, s99, v230
.LBB0_514:
	s_or_b64 exec, exec, s[8:9]
	v_add_u32_e32 v18, s3, v131
	v_cmp_gt_i32_e32 vcc, s10, v18
	s_and_saveexec_b64 s[8:9], vcc
	s_cbranch_execz .LBB0_516
	v_fma_f32 v16, v19, s99, v231
.LBB0_516:
	s_or_b64 exec, exec, s[8:9]
	v_add_u32_e32 v18, s3, v133
	v_cmp_gt_i32_e32 vcc, s10, v18
	v_mov_b32_e32 v18, 0xf149f2ca
	v_mov_b32_e32 v19, 0xf149f2ca
	s_and_saveexec_b64 s[8:9], vcc
	s_cbranch_execz .LBB0_518
	v_fma_f32 v19, v28, s99, v232
.LBB0_518:
	s_or_b64 exec, exec, s[8:9]
	v_add_u32_e32 v28, s3, v135
	v_cmp_gt_i32_e32 vcc, s10, v28
	s_and_saveexec_b64 s[8:9], vcc
	s_cbranch_execz .LBB0_520
	v_fma_f32 v18, v29, s99, v233
.LBB0_520:
	s_or_b64 exec, exec, s[8:9]
	v_add_u32_e32 v28, s3, v137
	v_cmp_gt_i32_e32 vcc, s10, v28
	v_mov_b32_e32 v28, 0xf149f2ca
	v_mov_b32_e32 v29, 0xf149f2ca
	s_and_saveexec_b64 s[8:9], vcc
	s_cbranch_execz .LBB0_522
	v_fma_f32 v29, v30, s99, v234
.LBB0_522:
	s_or_b64 exec, exec, s[8:9]
	v_add_u32_e32 v30, s3, v139
	v_cmp_gt_i32_e32 vcc, s10, v30
	s_and_saveexec_b64 s[8:9], vcc
	s_cbranch_execz .LBB0_524
	v_fma_f32 v28, v31, s99, v235
.LBB0_524:
	s_or_b64 exec, exec, s[8:9]
	v_add_u32_e32 v30, s3, v141
	v_cmp_gt_i32_e32 vcc, s10, v30
	v_mov_b32_e32 v30, 0xf149f2ca
	v_mov_b32_e32 v31, 0xf149f2ca
	s_and_saveexec_b64 s[8:9], vcc
	s_cbranch_execz .LBB0_526
	v_fma_f32 v31, v24, s99, v236
.LBB0_526:
	s_or_b64 exec, exec, s[8:9]
	v_add_u32_e32 v24, s3, v143
	v_cmp_gt_i32_e32 vcc, s10, v24
	s_and_saveexec_b64 s[8:9], vcc
	s_cbranch_execz .LBB0_528
	v_fma_f32 v30, v25, s99, v237
.LBB0_528:
	s_or_b64 exec, exec, s[8:9]
	v_add_u32_e32 v24, s3, v146
	v_cmp_gt_i32_e32 vcc, s10, v24
	v_mov_b32_e32 v24, 0xf149f2ca
	v_mov_b32_e32 v25, 0xf149f2ca
	s_and_saveexec_b64 s[8:9], vcc
	s_cbranch_execz .LBB0_530
	v_fma_f32 v25, v26, s99, v238
.LBB0_530:
	s_or_b64 exec, exec, s[8:9]
	v_add_u32_e32 v26, s3, v148
	v_cmp_gt_i32_e32 vcc, s10, v26
	s_and_saveexec_b64 s[8:9], vcc
	s_cbranch_execz .LBB0_532
	v_fma_f32 v24, v27, s99, v239
.LBB0_532:
	s_or_b64 exec, exec, s[8:9]
	v_add_u32_e32 v26, s3, v150
	v_cmp_gt_i32_e32 vcc, s10, v26
	s_and_b64 s[12:13], s[36:37], vcc
	v_mov_b32_e32 v26, 0xf149f2ca
	v_mov_b32_e32 v27, 0xf149f2ca
	s_and_saveexec_b64 s[8:9], s[12:13]
	s_cbranch_execz .LBB0_534
	v_fma_f32 v27, v12, s99, v240
.LBB0_534:
	s_or_b64 exec, exec, s[8:9]
	v_add_u32_e32 v12, s3, v152
	v_cmp_gt_i32_e32 vcc, s10, v12
	s_and_b64 s[12:13], s[38:39], vcc
	s_and_saveexec_b64 s[8:9], s[12:13]
	s_cbranch_execz .LBB0_536
	v_fma_f32 v26, v13, s99, v241
.LBB0_536:
	s_or_b64 exec, exec, s[8:9]
	v_add_u32_e32 v12, s3, v154
	v_cmp_gt_i32_e32 vcc, s10, v12
	s_and_b64 s[12:13], s[40:41], vcc
	v_mov_b32_e32 v12, 0xf149f2ca
	v_mov_b32_e32 v13, 0xf149f2ca
	s_and_saveexec_b64 s[8:9], s[12:13]
	s_cbranch_execz .LBB0_538
	v_fma_f32 v13, v14, s99, v244
.LBB0_538:
	s_or_b64 exec, exec, s[8:9]
	v_add_u32_e32 v14, s3, v156
	v_cmp_gt_i32_e32 vcc, s10, v14
	s_and_b64 s[12:13], s[42:43], vcc
	s_and_saveexec_b64 s[8:9], s[12:13]
	s_cbranch_execz .LBB0_540
	v_fma_f32 v12, v15, s99, v245
.LBB0_540:
	s_or_b64 exec, exec, s[8:9]
	v_add_u32_e32 v14, s3, v158
	v_cmp_gt_i32_e32 vcc, s10, v14
	s_and_b64 s[12:13], s[44:45], vcc
	v_mov_b32_e32 v14, 0xf149f2ca
	v_mov_b32_e32 v15, 0xf149f2ca
	s_and_saveexec_b64 s[8:9], s[12:13]
	s_cbranch_execz .LBB0_542
	v_fma_f32 v15, v8, s99, v246
.LBB0_542:
	s_or_b64 exec, exec, s[8:9]
	v_add_u32_e32 v8, s3, v160
	v_cmp_gt_i32_e32 vcc, s10, v8
	s_and_b64 s[12:13], s[46:47], vcc
	s_and_saveexec_b64 s[8:9], s[12:13]
	s_cbranch_execz .LBB0_544
	v_fma_f32 v14, v9, s99, v247
.LBB0_544:
	s_or_b64 exec, exec, s[8:9]
	v_add_u32_e32 v8, s3, v162
	v_cmp_gt_i32_e32 vcc, s10, v8
	s_and_b64 s[12:13], s[48:49], vcc
	v_mov_b32_e32 v8, 0xf149f2ca
	v_mov_b32_e32 v9, 0xf149f2ca
	s_and_saveexec_b64 s[8:9], s[12:13]
	s_cbranch_execz .LBB0_546
	v_fma_f32 v9, v10, s99, v248
.LBB0_546:
	s_or_b64 exec, exec, s[8:9]
	v_add_u32_e32 v10, s3, v164
	v_cmp_gt_i32_e32 vcc, s10, v10
	s_and_b64 s[12:13], s[50:51], vcc
	s_and_saveexec_b64 s[8:9], s[12:13]
	s_cbranch_execz .LBB0_548
	v_fma_f32 v8, v11, s99, v249
.LBB0_548:
	s_or_b64 exec, exec, s[8:9]
	v_add_u32_e32 v10, s3, v166
	v_cmp_gt_i32_e32 vcc, s10, v10
	s_and_b64 s[12:13], s[52:53], vcc
	v_mov_b32_e32 v10, 0xf149f2ca
	v_mov_b32_e32 v11, 0xf149f2ca
	s_and_saveexec_b64 s[8:9], s[12:13]
	s_cbranch_execz .LBB0_550
	v_fma_f32 v11, v4, s99, v250
.LBB0_550:
	s_or_b64 exec, exec, s[8:9]
	v_add_u32_e32 v4, s3, v168
	v_cmp_gt_i32_e32 vcc, s10, v4
	s_and_b64 s[12:13], s[54:55], vcc
	s_and_saveexec_b64 s[8:9], s[12:13]
	s_cbranch_execz .LBB0_552
	v_fma_f32 v10, v5, s99, v251
.LBB0_552:
	s_or_b64 exec, exec, s[8:9]
	v_add_u32_e32 v4, s3, v170
	v_cmp_gt_i32_e32 vcc, s10, v4
	s_and_b64 s[12:13], s[56:57], vcc
	v_mov_b32_e32 v4, 0xf149f2ca
	v_mov_b32_e32 v5, 0xf149f2ca
	s_and_saveexec_b64 s[8:9], s[12:13]
	s_cbranch_execz .LBB0_554
	v_fma_f32 v5, v6, s99, v252
.LBB0_554:
	s_or_b64 exec, exec, s[8:9]
	v_add_u32_e32 v6, s3, v172
	v_cmp_gt_i32_e32 vcc, s10, v6
	s_and_b64 s[12:13], s[58:59], vcc
	s_and_saveexec_b64 s[8:9], s[12:13]
	s_cbranch_execz .LBB0_556
	v_fma_f32 v4, v7, s99, v253
.LBB0_556:
	s_or_b64 exec, exec, s[8:9]
	v_add_u32_e32 v6, s3, v174
	v_cmp_gt_i32_e32 vcc, s10, v6
	s_and_b64 s[12:13], s[60:61], vcc
	v_mov_b32_e32 v6, 0xf149f2ca
	v_mov_b32_e32 v7, 0xf149f2ca
	s_and_saveexec_b64 s[8:9], s[12:13]
	s_cbranch_execz .LBB0_558
	v_fma_f32 v7, v0, s99, v254
.LBB0_558:
	s_or_b64 exec, exec, s[8:9]
	v_add_u32_e32 v0, s3, v176
	v_cmp_gt_i32_e32 vcc, s10, v0
	s_and_b64 s[12:13], s[62:63], vcc
	s_and_saveexec_b64 s[8:9], s[12:13]
	s_cbranch_execz .LBB0_560
	v_fma_f32 v6, v1, s99, v255
